# v10: + static s_setprio 1 for waves 4-7 in GEMM1 and merge-gate K-loops
# speedup vs baseline: 1.0336x; 1.0033x over previous
.LBB0_60:
.LBB0_61:
	v_readfirstlane_b32 s7, v98
	s_nop 0
	s_cmpk_lt_u32 s7, 0x1000
	s_cbranch_scc1 .Lgg_noprio
	s_setprio 1
.Lgg_noprio:
	s_mul_i32 s69, s68, 0xc000
	s_add_i32 s8, s68, -1
	s_cmp_eq_u32 s68, 0
	s_cselect_b32 s8, 2, s8
	s_mul_i32 s8, s8, 0xc000
	s_add_i32 s6, s8, s7
	v_add3_u32 v238, s69, v101, v100
	v_add3_u32 v239, s69, v99, v100
	ds_read_b128 v[132:135], v238 offset:0
	ds_read_b128 v[116:119], v239 offset:32768
	ds_read_b128 v[120:123], v239 offset:34816
	ds_read_b128 v[136:139], v238 offset:2048
	ds_read_b128 v[140:143], v238 offset:4096
	ds_read_b128 v[144:147], v238 offset:6144
	ds_read_b128 v[214:217], v238 offset:8192
	ds_read_b128 v[218:221], v238 offset:10240

.Lgg_tail:
	v_mfma_f32_16x16x32_bf16 v[26:29], v[234:237], v[124:127], v[26:29]
	v_mfma_f32_16x16x32_bf16 v[2:5], v[234:237], v[128:131], v[2:5]
	s_setprio 0

.LBB0_328:
.LBB0_329:
	v_readfirstlane_b32 s8, v212
	v_readfirstlane_b32 s9, v213
	v_readfirstlane_b32 s14, v210
	v_readfirstlane_b32 s15, v211
	v_readfirstlane_b32 s18, v165
	s_nop 1
	s_cmpk_lt_u32 s18, 0x1000
	s_cbranch_scc1 .Lg1_noprio
	s_setprio 1
.Lg1_noprio:
	v_subrev_u32_e32 v173, s8, v212
	v_subrev_u32_e32 v175, s8, v208
	v_subrev_u32_e32 v177, s8, v204
	v_subrev_u32_e32 v179, s8, v200
	v_subrev_u32_e32 v181, s14, v210
	v_subrev_u32_e32 v183, s14, v206
	v_subrev_u32_e32 v185, s14, v202
	v_subrev_u32_e32 v241, s14, v198
	s_and_b32 s16, s5, 0x10000
	v_add3_u32 v187, s16, v171, v169
	v_add3_u32 v0, s16, v167, v169
	ds_read_b128 v[146:149], v187 offset:0
	ds_read_b128 v[130:133], v0 offset:32768
	ds_read_b128 v[134:137], v0 offset:34816
	ds_read_b128 v[138:141], v0 offset:36864
	ds_read_b128 v[142:145], v0 offset:38912
	ds_read_b128 v[150:153], v187 offset:2048
	ds_read_b128 v[154:157], v187 offset:4096
	s_xor_b32 s17, s16, 0x10000
	s_add_i32 s17, s17, s18

.Lg1_tail:
	v_mfma_f32_16x16x32_bf16 v[6:9], v[242:245], v[198:201], v[6:9]
	v_mfma_f32_16x16x32_bf16 v[2:5], v[242:245], v[202:205], v[2:5]
	v_mfma_f32_16x16x32_bf16 v[26:29], v[242:245], v[206:209], v[26:29]
	v_mfma_f32_16x16x32_bf16 v[62:65], v[242:245], v[210:213], v[62:65]
	s_setprio 0
